# stack3 + seam 3: waves 1-7 warm L2 with the first attention unit's q rows after arrival (overlaps the P4-start q burst with the barrier wait)
# baseline (speedup 1.0000x reference)
.LBB0_586:
	s_cmp_gt_i32 s89, 4
	s_cselect_b64 s[4:5], -1, 0
	s_and_b64 s[0:1], s[2:3], s[4:5]
	s_andn2_b64 vcc, exec, s[0:1]
	s_cbranch_vccnz .LBB0_640
	s_waitcnt vmcnt(0)
	s_waitcnt vmcnt(0)
	s_barrier
	v_readfirstlane_b32 s40, v0
	s_lshr_b32 s40, s40, 6
	s_cmp_eq_u32 s40, 0
	s_cbranch_scc1 .Lqpf_skip
	s_lshr_b32 s41, s93, 4
	s_and_b32 s42, s93, 15
	s_sub_i32 s42, 31, s42
	s_lshr_b32 s43, s41, 2
	s_and_b32 s41, s41, 3
	s_lshl_b32 s41, s41, 2
	s_lshr_b32 s44, s40, 1
	s_add_i32 s41, s41, s44
	s_and_b32 s44, s40, 1
	s_lshl_b32 s43, s43, 11
	s_lshl_b32 s42, s42, 6
	s_lshl_b32 s44, s44, 5
	s_add_i32 s43, s43, s42
	s_add_i32 s43, s43, s44
	v_and_b32_e32 v2, 31, v0
	v_add_u32_e32 v2, s43, v2
	v_mov_b32_e32 v3, 0
	v_lshlrev_b64 v[2:3], 12, v[2:3]
	v_bfe_u32 v4, v0, 5, 1
	v_lshlrev_b32_e32 v4, 4, v4
	s_lshl_b32 s41, s41, 8
	v_add_u32_e32 v4, s41, v4
	v_mov_b32_e32 v5, 0
	v_lshl_add_u64 v[2:3], v[2:3], 0, v[4:5]
	s_add_u32 s44, s76, 0x8933400
	s_addc_u32 s45, s77, 0
	v_lshl_add_u64 v[2:3], s[44:45], 0, v[2:3]
	global_load_dwordx4 v[6:9], v[2:3], off
	global_load_dwordx4 v[10:13], v[2:3], off offset:32
	global_load_dwordx4 v[14:17], v[2:3], off offset:64
	global_load_dwordx4 v[18:21], v[2:3], off offset:96
	global_load_dwordx4 v[22:25], v[2:3], off offset:128
	global_load_dwordx4 v[26:29], v[2:3], off offset:160
	global_load_dwordx4 v[30:33], v[2:3], off offset:192
	global_load_dwordx4 v[34:37], v[2:3], off offset:224
.Lqpf_skip:
	s_and_saveexec_b64 s[2:3], s[84:85]
	s_cbranch_execz .LBB0_639
	s_add_i32 s0, 0, 0x23e20
	v_mov_b32_e32 v2, s0
	s_waitcnt vmcnt(0) expcnt(0) lgkmcnt(0)
	ds_read_b32 v4, v2
	s_add_i32 s0, 0, 0x23e24
	v_mov_b32_e32 v2, s0
	ds_read_b32 v2, v2
	s_waitcnt lgkmcnt(1)
	v_cmp_ne_u32_e32 vcc, 0, v4
	s_cbranch_vccnz .LBB0_603
	s_add_u32 s6, s76, 0x1000
	s_load_dwordx2 s[0:1], s[86:87], 0x4
	s_addc_u32 s7, s77, 0
	s_add_u32 s8, s76, 0x1100
	s_addc_u32 s9, s77, 0
	s_add_u32 s10, s76, 0x1200
	s_addc_u32 s11, s77, 0
	s_waitcnt lgkmcnt(0)
	s_mul_i32 s0, s0, s79
	s_add_u32 s12, s76, 0x1300
	s_mul_i32 s0, s0, s1
	s_addc_u32 s13, s77, 0
	s_mov_b32 s1, 1
	v_mov_b32_e32 v18, 0
	s_branch .LBB0_591

.LBB0_639:
	s_or_b64 exec, exec, s[2:3]
	s_waitcnt lgkmcnt(0)
	s_waitcnt vmcnt(0)
	s_barrier
